# RG-LRU phase: per-chunk input wait no longer waits for the chunk's own output stores (counted vmcnt)
# speedup vs baseline: 1.0213x; 1.0142x over previous
.LBB0_377:
	s_or_b64 exec, exec, s[0:1]
	v_mov_b32_e32 v27, v1
	v_lshl_add_u64 v[32:33], s[84:85], 0, v[26:27]
	v_lshl_add_u64 v[26:27], s[82:83], 0, v[26:27]
	v_mov_b32_e32 v25, v1
	v_lshl_add_u64 v[112:113], v[0:1], 1, v[26:27]
	v_lshlrev_b32_e32 v0, 1, v2
	v_lshl_add_u64 v[108:109], v[26:27], 0, v[24:25]
	v_lshl_add_u64 v[116:117], v[26:27], 0, v[0:1]
	v_add_u32_e32 v27, v86, v30
	v_lshrrev_b32_e32 v24, 5, v27
	v_mul_u32_u24_e32 v202, 0x8080, v24
	v_and_b32_e32 v24, 28, v27
	v_lshlrev_b32_e32 v24, 1, v24
	v_lshl_add_u64 v[120:121], s[86:87], 0, v[24:25]
	v_add_u32_e32 v24, 16, v27
	v_lshrrev_b32_e32 v25, 5, v24
	v_and_b32_e32 v24, 28, v24
	v_mul_u32_u24_e32 v203, 0x8080, v25
	v_lshlrev_b32_e32 v24, 1, v24
	v_mov_b32_e32 v25, v1
	v_lshl_add_u64 v[122:123], s[86:87], 0, v[24:25]
	v_add_u32_e32 v24, 32, v27
	v_sub_u32_e32 v0, v139, v29
	v_lshrrev_b32_e32 v25, 5, v24
	v_and_b32_e32 v24, 28, v24
	v_cmp_gt_u32_e64 s[42:43], 48, v0
	v_lshl_add_u32 v26, v0, 2, 0
	v_cndmask_b32_e64 v0, v184, v185, s[30:31]
	v_mul_u32_u24_e32 v204, 0x8080, v25
	v_lshlrev_b32_e32 v24, 1, v24
	v_mov_b32_e32 v25, v1
	v_cndmask_b32_e64 v195, 64, 16, s[30:31]
	v_mul_u32_u24_e32 v2, 0x4200, v31
	v_mov_b32_e32 v3, v1
	v_lshl_add_u64 v[126:127], s[86:87], 0, v[24:25]
	v_lshl_add_u64 v[24:25], s[88:89], 0, v[0:1]
	v_cndmask_b32_e64 v194, 64, 1, s[30:31]
	v_cmp_lt_u32_e64 s[48:49], v142, v195
	v_cmp_gt_u32_e64 s[0:1], 56, v86
	v_lshl_add_u64 v[2:3], v[24:25], 0, v[2:3]
	v_mov_b32_e32 v91, v1
	v_lshl_add_u64 v[106:107], v[72:73], 1, v[32:33]
	v_lshl_add_u64 v[110:111], v[74:75], 1, v[32:33]
	v_lshl_add_u64 v[114:115], v[76:77], 1, v[32:33]
	v_add_u32_e32 v201, -1, v194
	s_mov_b32 s33, 0
	v_cmp_ne_u32_e64 s[44:45], 0, v28
	v_cmp_ge_u32_e64 s[46:47], v142, v195
	s_and_b64 s[92:93], s[0:1], s[48:49]
	v_lshl_add_u64 v[128:129], v[2:3], 0, v[90:91]
	s_mov_b64 s[96:97], 0
	v_add_u32_e32 v91, v26, v154
	v_add_u32_e32 v205, v26, v156
	s_waitcnt vmcnt(0)
	s_mov_b32 s98, 0
	s_branch .LBB0_379
.LBB0_378:
	s_or_b64 exec, exec, s[0:1]
	v_cmp_eq_u32_e64 s[0:1], s10, v194
	s_waitcnt lgkmcnt(0)
	v_pk_fma_f32 v[92:93], v[2:3], v[32:33], v[28:29]
	v_pk_fma_f32 v[94:95], v[4:5], v[6:7], v[30:31]
	v_pk_fma_f32 v[4:5], v[8:9], v[62:63], v[24:25]
	v_pk_fma_f32 v[6:7], v[10:11], v[60:61], v[26:27]
	v_pk_fma_f32 v[8:9], v[48:49], v[58:59], v[52:53]
	v_pk_fma_f32 v[10:11], v[50:51], v[56:57], v[54:55]
	s_or_b64 s[96:97], s[0:1], s[96:97]
	s_cmp_lt_u32 s98, 2
	s_cbranch_scc1 .Lvm_lo
	s_cmp_eq_u32 s98, 2
	s_cbranch_scc1 .Lvm_2
	s_waitcnt vmcnt(3)
	s_branch .Lvm_done
.Lvm_2:
	s_waitcnt vmcnt(2)
	s_branch .Lvm_done
.Lvm_lo:
	s_cmp_eq_u32 s98, 0
	s_cbranch_scc1 .Lvm_0
	s_waitcnt vmcnt(1)
	s_branch .Lvm_done

.Lvm_done:
	s_mov_b32 s98, 0
	v_mov_b64_e32 v[124:125], v[134:135]
	v_mov_b64_e32 v[130:131], v[132:133]
	s_mov_b32 s33, s10
	v_mov_b32_e32 v118, v136
	v_mov_b32_e32 v119, v137
	s_andn2_b64 exec, exec, s[96:97]
	s_cbranch_execz .LBB0_501

.LBB0_382:
	ds_write_b128 v186, v[20:23] offset:8192
.LBB0_383:
	s_or_b64 exec, exec, s[0:1]
	s_add_i32 s10, s33, 1
	v_cmp_lt_u32_e64 s[0:1], s10, v194
	v_mov_b32_e32 v137, v119
	v_mov_b32_e32 v136, v118
	v_mov_b64_e32 v[132:133], v[130:131]
	v_mov_b64_e32 v[134:135], v[124:125]
	s_waitcnt lgkmcnt(0)
	s_barrier
	s_and_saveexec_b64 s[52:53], s[0:1]
	s_cbranch_execz .LBB0_403
	v_mov_b32_e32 v2, v1
	v_mov_b32_e32 v3, v1
	s_lshl_b32 s74, s10, 6
	v_mov_b32_e32 v0, v1
	v_mov_b64_e32 v[14:15], v[2:3]
	s_add_i32 s11, s74, -3
	v_mov_b64_e32 v[12:13], v[0:1]
	s_and_saveexec_b64 s[50:51], s[8:9]
	s_cbranch_execz .LBB0_388
	v_mov_b32_e32 v2, v1
	v_mov_b32_e32 v3, v1
	v_add_u32_e32 v16, s11, v140
	v_mov_b32_e32 v0, v1
	v_mov_b64_e32 v[14:15], v[2:3]
	v_cmp_lt_u32_e64 s[0:1], v16, v83
	v_mov_b64_e32 v[12:13], v[0:1]
	s_and_saveexec_b64 s[72:73], s[0:1]
	s_cbranch_execz .LBB0_387
	v_add_u32_e32 v0, v16, v192
	v_mad_u64_u32 v[2:3], s[0:1], v0, s78, v[106:107]
	global_load_dwordx4 v[12:15], v[2:3], off

.LBB0_493:
	s_or_b64 exec, exec, s[0:1]
	s_waitcnt lgkmcnt(0)
	s_barrier
	ds_read_b128 v[48:51], v150 offset:37984
	ds_read_b128 v[52:55], v150 offset:38752
	ds_read_b128 v[68:71], v150 offset:38176
	ds_read_b128 v[206:209], v150 offset:38944
	ds_read_b128 v[210:213], v150 offset:38368
	ds_read_b128 v[214:217], v150 offset:39136
	s_waitcnt lgkmcnt(4)
	v_pk_fma_f32 v[60:61], v[48:49], v[8:9], v[52:53]
	v_pk_fma_f32 v[64:65], v[50:51], v[10:11], v[54:55]
	ds_read_b128 v[48:51], v150 offset:38560
	ds_read_b128 v[52:55], v150 offset:39328
	s_waitcnt lgkmcnt(4)
	v_pk_fma_f32 v[2:3], v[68:69], v[60:61], v[206:207]
	v_pk_fma_f32 v[62:63], v[70:71], v[64:65], v[208:209]
	v_lshl_add_u32 v66, s33, 6, v193
	s_waitcnt lgkmcnt(2)
	v_pk_fma_f32 v[58:59], v[210:211], v[2:3], v[214:215]
	v_pk_fma_f32 v[56:57], v[212:213], v[62:63], v[216:217]
	s_and_saveexec_b64 s[0:1], s[48:49]
	s_cbranch_execz .LBB0_495
	v_cndmask_b32_e64 v10, 0, v10, s[20:21]
	v_cndmask_b32_e64 v9, 0, v9, s[20:21]
	v_cndmask_b32_e64 v8, 0, v8, s[20:21]
	v_cndmask_b32_e64 v8, v8, v60, s[22:23]
	v_cndmask_b32_e64 v9, v9, v61, s[22:23]
	v_cndmask_b32_e64 v10, v10, v64, s[22:23]
	v_cndmask_b32_e64 v0, 0, v11, s[20:21]
	v_cndmask_b32_e64 v10, v10, v62, s[24:25]
	v_cndmask_b32_e64 v3, v9, v3, s[24:25]
	v_cndmask_b32_e64 v2, v8, v2, s[24:25]
	v_cndmask_b32_e64 v0, v0, v65, s[22:23]
	v_cndmask_b32_e64 v2, v2, v58, s[26:27]
	v_cndmask_b32_e64 v3, v3, v59, s[26:27]
	v_cndmask_b32_e64 v8, v10, v56, s[26:27]
	v_cndmask_b32_e64 v0, v0, v63, s[24:25]
	v_fmac_f32_e32 v26, v30, v8
	v_fma_f32 v3, v29, v3, v25
	v_fmac_f32_e32 v24, v28, v2
	v_lshlrev_b32_e32 v2, 16, v130
	v_and_b32_e32 v8, 0xffff0000, v130
	v_cndmask_b32_e64 v0, v0, v57, s[26:27]
	v_mul_f32_e32 v2, v24, v2
	v_mul_f32_e32 v3, v3, v8
	v_fma_f32 v0, v31, v0, v27
	v_cvt_pk_bf16_f32 v2, v2, v3
	v_lshlrev_b32_e32 v3, 16, v131
	v_and_b32_e32 v8, 0xffff0000, v131
	v_mul_f32_e32 v3, v26, v3
	v_mul_f32_e32 v0, v0, v8
	v_cvt_pk_bf16_f32 v3, v3, v0
	v_add_u32_e32 v0, v66, v202
	v_lshlrev_b64 v[8:9], 6, v[0:1]
	v_lshl_add_u64 v[8:9], v[120:121], 0, v[8:9]
	global_store_dwordx2 v[8:9], v[2:3], off
	s_add_u32 s98, s98, 1
.LBB0_495:
	s_or_b64 exec, exec, s[0:1]
	ds_read_b128 v[8:11], v150 offset:38048
	ds_read_b128 v[24:27], v150 offset:38816
	ds_read_b128 v[68:71], v150 offset:38240
	ds_read_b128 v[206:209], v150 offset:39008
	ds_read_b128 v[210:213], v150 offset:38432
	ds_read_b128 v[214:217], v150 offset:39200
	s_waitcnt lgkmcnt(4)
	v_pk_fma_f32 v[28:29], v[8:9], v[4:5], v[24:25]
	v_pk_fma_f32 v[64:65], v[10:11], v[6:7], v[26:27]
	ds_read_b128 v[8:11], v150 offset:38624
	ds_read_b128 v[24:27], v150 offset:39392
	s_waitcnt lgkmcnt(4)
	v_pk_fma_f32 v[2:3], v[68:69], v[28:29], v[206:207]
	v_pk_fma_f32 v[30:31], v[70:71], v[64:65], v[208:209]
	s_waitcnt lgkmcnt(2)
	v_pk_fma_f32 v[62:63], v[210:211], v[2:3], v[214:215]
	v_pk_fma_f32 v[60:61], v[212:213], v[30:31], v[216:217]
	s_and_saveexec_b64 s[0:1], s[48:49]
	s_cbranch_execz .LBB0_497
	v_cndmask_b32_e64 v6, 0, v6, s[20:21]
	v_cndmask_b32_e64 v5, 0, v5, s[20:21]
	v_cndmask_b32_e64 v4, 0, v4, s[20:21]
	v_cndmask_b32_e64 v4, v4, v28, s[22:23]
	v_cndmask_b32_e64 v5, v5, v29, s[22:23]
	v_cndmask_b32_e64 v6, v6, v64, s[22:23]
	v_cndmask_b32_e64 v0, 0, v7, s[20:21]
	v_cndmask_b32_e64 v6, v6, v30, s[24:25]
	v_cndmask_b32_e64 v3, v5, v3, s[24:25]
	v_cndmask_b32_e64 v2, v4, v2, s[24:25]
	v_cndmask_b32_e64 v0, v0, v65, s[22:23]
	v_cndmask_b32_e64 v2, v2, v62, s[26:27]
	v_cndmask_b32_e64 v3, v3, v63, s[26:27]
	v_cndmask_b32_e64 v4, v6, v60, s[26:27]
	v_cndmask_b32_e64 v0, v0, v31, s[24:25]
	v_fmac_f32_e32 v34, v38, v4
	v_fma_f32 v3, v37, v3, v33
	v_fmac_f32_e32 v32, v36, v2
	v_lshlrev_b32_e32 v2, 16, v124
	v_and_b32_e32 v4, 0xffff0000, v124
	v_cndmask_b32_e64 v0, v0, v61, s[26:27]
	v_mul_f32_e32 v2, v32, v2
	v_mul_f32_e32 v3, v3, v4
	v_fma_f32 v0, v39, v0, v35
	v_cvt_pk_bf16_f32 v2, v2, v3
	v_lshlrev_b32_e32 v3, 16, v125
	v_and_b32_e32 v4, 0xffff0000, v125
	v_mul_f32_e32 v3, v34, v3
	v_mul_f32_e32 v0, v0, v4
	v_cvt_pk_bf16_f32 v3, v3, v0
	v_add_u32_e32 v0, v66, v203
	v_lshlrev_b64 v[4:5], 6, v[0:1]
	v_lshl_add_u64 v[4:5], v[122:123], 0, v[4:5]
	global_store_dwordx2 v[4:5], v[2:3], off
	s_add_u32 s98, s98, 1
.LBB0_497:
	s_or_b64 exec, exec, s[0:1]
	ds_read_b128 v[2:5], v150 offset:38112
	ds_read_b128 v[28:31], v150 offset:38880
	ds_read_b128 v[68:71], v150 offset:38304
	ds_read_b128 v[206:209], v150 offset:39072
	ds_read_b128 v[210:213], v150 offset:38496
	ds_read_b128 v[214:217], v150 offset:39264
	s_waitcnt lgkmcnt(4)
	v_pk_fma_f32 v[36:37], v[2:3], v[92:93], v[28:29]
	v_pk_fma_f32 v[64:65], v[4:5], v[94:95], v[30:31]
	ds_read_b128 v[2:5], v150 offset:38688
	ds_read_b128 v[28:31], v150 offset:39456
	s_waitcnt lgkmcnt(4)
	v_pk_fma_f32 v[34:35], v[68:69], v[36:37], v[206:207]
	v_pk_fma_f32 v[38:39], v[70:71], v[64:65], v[208:209]
	s_waitcnt lgkmcnt(2)
	v_pk_fma_f32 v[32:33], v[210:211], v[34:35], v[214:215]
	v_pk_fma_f32 v[6:7], v[212:213], v[38:39], v[216:217]
	s_and_saveexec_b64 s[0:1], s[92:93]
	s_cbranch_execz .LBB0_378
	v_cndmask_b32_e64 v67, 0, v94, s[20:21]
	v_cndmask_b32_e64 v68, 0, v93, s[20:21]
	v_cndmask_b32_e64 v69, 0, v92, s[20:21]
	v_cndmask_b32_e64 v36, v69, v36, s[22:23]
	v_cndmask_b32_e64 v37, v68, v37, s[22:23]
	v_cndmask_b32_e64 v64, v67, v64, s[22:23]
	v_cndmask_b32_e64 v0, 0, v95, s[20:21]
	v_cndmask_b32_e64 v38, v64, v38, s[24:25]
	v_cndmask_b32_e64 v35, v37, v35, s[24:25]
	v_cndmask_b32_e64 v34, v36, v34, s[24:25]
	v_cndmask_b32_e64 v0, v0, v65, s[22:23]
	v_cndmask_b32_e64 v34, v34, v32, s[26:27]
	v_cndmask_b32_e64 v35, v35, v33, s[26:27]
	v_cndmask_b32_e64 v36, v38, v6, s[26:27]
	v_cndmask_b32_e64 v0, v0, v39, s[24:25]
	v_fmac_f32_e32 v42, v46, v36
	v_fma_f32 v35, v45, v35, v41
	v_fmac_f32_e32 v40, v44, v34
	v_lshlrev_b32_e32 v34, 16, v118
	v_and_b32_e32 v36, 0xffff0000, v118
	v_cndmask_b32_e64 v0, v0, v7, s[26:27]
	v_mul_f32_e32 v34, v40, v34
	v_mul_f32_e32 v35, v35, v36
	v_fma_f32 v0, v47, v0, v43
	v_cvt_pk_bf16_f32 v34, v34, v35
	v_lshlrev_b32_e32 v35, 16, v119
	v_and_b32_e32 v36, 0xffff0000, v119
	v_mul_f32_e32 v35, v42, v35
	v_mul_f32_e32 v0, v0, v36
	v_cvt_pk_bf16_f32 v35, v35, v0
	v_add_u32_e32 v0, v66, v204
	v_lshlrev_b64 v[36:37], 6, v[0:1]
	v_lshl_add_u64 v[36:37], v[126:127], 0, v[36:37]
	global_store_dwordx2 v[36:37], v[34:35], off
	s_add_u32 s98, s98, 1
	s_branch .LBB0_378
.LBB0_499:
	ds_write_b128 v186, v[12:15]
	s_or_b64 exec, exec, s[0:1]
	s_and_saveexec_b64 s[0:1], s[12:13]
	s_cbranch_execz .LBB0_381
.LBB0_500:
	ds_write_b128 v174, v[16:19]
	s_or_b64 exec, exec, s[0:1]
	s_and_saveexec_b64 s[0:1], s[14:15]
	s_cbranch_execnz .LBB0_382
	s_branch .LBB0_383
